# software-pipelined out-projection epilogue: 6 row-chunks of residual loads in flight with counted vmcnt, norm-weight loads hoisted, row sums reduced once at the end
# baseline (speedup 1.0000x reference)
.LBB0_1063:
	v_lshl_add_u32 v156, s40, 8, v152
	v_lshl_or_b32 v157, s35, 8, v154
	v_lshlrev_b32_e32 v144, 2, v157
	v_lshl_add_u32 v240, v156, 13, v144
	v_mov_b32_e32 v241, v240
	v_readlane_b32 s34, v251, 12
	v_readlane_b32 s35, v251, 13
	v_readlane_b32 s2, v254, 32
	s_nop 0
	s_cmp_eq_u32 s2, 0
	s_cbranch_scc1 .Lout_plain
	v_readlane_b32 s2, v253, 14
	v_readlane_b32 s3, v253, 15
	v_readlane_b32 s20, v251, 10
	v_readlane_b32 s21, v251, 11
	v_readlane_b32 s18, v253, 16
	v_readlane_b32 s19, v253, 17
	s_nop 3
	global_load_dwordx4 v[228:231], v144, s[2:3]
	global_load_dwordx4 v[232:235], v144, s[2:3] offset:16
	global_load_dwordx4 v[236:239], v144, s[2:3] offset:512
	global_load_dwordx4 v[140:143], v144, s[2:3] offset:528
	global_load_dwordx4 v[156:159], v240, s[6:7]
	global_load_dwordx4 v[160:163], v240, s[6:7] offset:16
	global_load_dwordx4 v[164:167], v240, s[6:7] offset:512
	global_load_dwordx4 v[168:171], v240, s[6:7] offset:528
	v_add_u32_e32 v240, 0x20000, v240
	global_load_dwordx4 v[172:175], v240, s[6:7]
	global_load_dwordx4 v[176:179], v240, s[6:7] offset:16
	global_load_dwordx4 v[180:183], v240, s[6:7] offset:512
	global_load_dwordx4 v[184:187], v240, s[6:7] offset:528
	v_add_u32_e32 v240, 0x20000, v240
	global_load_dwordx4 v[188:191], v240, s[6:7]
	global_load_dwordx4 v[192:195], v240, s[6:7] offset:16
	global_load_dwordx4 v[196:199], v240, s[6:7] offset:512
	global_load_dwordx4 v[224:227], v240, s[6:7] offset:528
	v_add_u32_e32 v240, 0x20000, v240
	v_mov_b32_e32 v144, 0
	v_mov_b32_e32 v145, 0
	v_mov_b32_e32 v146, 0
	v_mov_b32_e32 v147, 0
	v_mov_b32_e32 v148, 0
	v_mov_b32_e32 v149, 0
	v_mov_b32_e32 v150, 0
	v_mov_b32_e32 v151, 0
	s_waitcnt vmcnt(10)
	v_pk_add_f32 v[126:127], v[126:127], v[156:157]
	v_pk_add_f32 v[128:129], v[128:129], v[158:159]
	v_pk_add_f32 v[122:123], v[122:123], v[160:161]
	v_pk_add_f32 v[124:125], v[124:125], v[162:163]
	global_store_dwordx4 v241, v[126:129], s[34:35]
	global_store_dwordx4 v241, v[122:125], s[34:35] offset:16
	v_fmac_f32_e32 v144, v126, v126
	v_fmac_f32_e32 v144, v127, v127
	v_fmac_f32_e32 v144, v128, v128
	v_fmac_f32_e32 v144, v129, v129
	v_fmac_f32_e32 v144, v122, v122
	v_fmac_f32_e32 v144, v123, v123
	v_fmac_f32_e32 v144, v124, v124
	v_fmac_f32_e32 v144, v125, v125
	v_pk_mul_f32 v[156:157], v[126:127], v[228:229]
	v_pk_mul_f32 v[158:159], v[128:129], v[230:231]
	v_pk_mul_f32 v[160:161], v[122:123], v[232:233]
	v_pk_mul_f32 v[162:163], v[124:125], v[234:235]
	v_cvt_pk_bf16_f32 v156, v156, v157
	v_cvt_pk_bf16_f32 v157, v158, v159
	v_cvt_pk_bf16_f32 v158, v160, v161
	v_cvt_pk_bf16_f32 v159, v162, v163
	v_lshrrev_b32_e32 v160, 1, v241
	global_store_dwordx4 v160, v[156:159], s[20:21]
	s_nop 0
	global_load_dwordx4 v[156:159], v240, s[6:7]
	global_load_dwordx4 v[160:163], v240, s[6:7] offset:16
	s_waitcnt vmcnt(13)
	v_pk_add_f32 v[118:119], v[118:119], v[164:165]
	v_pk_add_f32 v[120:121], v[120:121], v[166:167]
	v_pk_add_f32 v[114:115], v[114:115], v[168:169]
	v_pk_add_f32 v[116:117], v[116:117], v[170:171]
	global_store_dwordx4 v241, v[118:121], s[34:35] offset:512
	global_store_dwordx4 v241, v[114:117], s[34:35] offset:528
	v_fmac_f32_e32 v144, v118, v118
	v_fmac_f32_e32 v144, v119, v119
	v_fmac_f32_e32 v144, v120, v120
	v_fmac_f32_e32 v144, v121, v121
	v_fmac_f32_e32 v144, v114, v114
	v_fmac_f32_e32 v144, v115, v115
	v_fmac_f32_e32 v144, v116, v116
	v_fmac_f32_e32 v144, v117, v117
	v_pk_mul_f32 v[164:165], v[118:119], v[236:237]
	v_pk_mul_f32 v[166:167], v[120:121], v[238:239]
	v_pk_mul_f32 v[168:169], v[114:115], v[140:141]
	v_pk_mul_f32 v[170:171], v[116:117], v[142:143]
	v_cvt_pk_bf16_f32 v164, v164, v165
	v_cvt_pk_bf16_f32 v165, v166, v167
	v_cvt_pk_bf16_f32 v166, v168, v169
	v_cvt_pk_bf16_f32 v167, v170, v171
	v_lshrrev_b32_e32 v168, 1, v241
	global_store_dwordx4 v168, v[164:167], s[20:21] offset:256
	v_add_u32_e32 v241, 0x20000, v241
	global_load_dwordx4 v[164:167], v240, s[6:7] offset:512
	global_load_dwordx4 v[168:171], v240, s[6:7] offset:528
	v_add_u32_e32 v240, 0xa0000, v240
	s_waitcnt vmcnt(16)
	v_pk_add_f32 v[110:111], v[110:111], v[172:173]
	v_pk_add_f32 v[112:113], v[112:113], v[174:175]
	v_pk_add_f32 v[106:107], v[106:107], v[176:177]
	v_pk_add_f32 v[108:109], v[108:109], v[178:179]
	global_store_dwordx4 v241, v[110:113], s[34:35]
	global_store_dwordx4 v241, v[106:109], s[34:35] offset:16
	v_fmac_f32_e32 v145, v110, v110
	v_fmac_f32_e32 v145, v111, v111
	v_fmac_f32_e32 v145, v112, v112
	v_fmac_f32_e32 v145, v113, v113
	v_fmac_f32_e32 v145, v106, v106
	v_fmac_f32_e32 v145, v107, v107
	v_fmac_f32_e32 v145, v108, v108
	v_fmac_f32_e32 v145, v109, v109
	v_pk_mul_f32 v[172:173], v[110:111], v[228:229]
	v_pk_mul_f32 v[174:175], v[112:113], v[230:231]
	v_pk_mul_f32 v[176:177], v[106:107], v[232:233]
	v_pk_mul_f32 v[178:179], v[108:109], v[234:235]
	v_cvt_pk_bf16_f32 v172, v172, v173
	v_cvt_pk_bf16_f32 v173, v174, v175
	v_cvt_pk_bf16_f32 v174, v176, v177
	v_cvt_pk_bf16_f32 v175, v178, v179
	v_lshrrev_b32_e32 v176, 1, v241
	global_store_dwordx4 v176, v[172:175], s[20:21]
	s_nop 0
	global_load_dwordx4 v[172:175], v240, s[6:7]
	global_load_dwordx4 v[176:179], v240, s[6:7] offset:16
	s_waitcnt vmcnt(19)
	v_pk_add_f32 v[102:103], v[102:103], v[180:181]
	v_pk_add_f32 v[104:105], v[104:105], v[182:183]
	v_pk_add_f32 v[98:99], v[98:99], v[184:185]
	v_pk_add_f32 v[100:101], v[100:101], v[186:187]
	global_store_dwordx4 v241, v[102:105], s[34:35] offset:512
	global_store_dwordx4 v241, v[98:101], s[34:35] offset:528
	v_fmac_f32_e32 v145, v102, v102
	v_fmac_f32_e32 v145, v103, v103
	v_fmac_f32_e32 v145, v104, v104
	v_fmac_f32_e32 v145, v105, v105
	v_fmac_f32_e32 v145, v98, v98
	v_fmac_f32_e32 v145, v99, v99
	v_fmac_f32_e32 v145, v100, v100
	v_fmac_f32_e32 v145, v101, v101
	v_pk_mul_f32 v[180:181], v[102:103], v[236:237]
	v_pk_mul_f32 v[182:183], v[104:105], v[238:239]
	v_pk_mul_f32 v[184:185], v[98:99], v[140:141]
	v_pk_mul_f32 v[186:187], v[100:101], v[142:143]
	v_cvt_pk_bf16_f32 v180, v180, v181
	v_cvt_pk_bf16_f32 v181, v182, v183
	v_cvt_pk_bf16_f32 v182, v184, v185
	v_cvt_pk_bf16_f32 v183, v186, v187
	v_lshrrev_b32_e32 v184, 1, v241
	global_store_dwordx4 v184, v[180:183], s[20:21] offset:256
	v_add_u32_e32 v241, 0x20000, v241
	global_load_dwordx4 v[180:183], v240, s[6:7] offset:512
	global_load_dwordx4 v[184:187], v240, s[6:7] offset:528
	v_add_u32_e32 v240, 0x20000, v240
	s_waitcnt vmcnt(22)
	v_pk_add_f32 v[94:95], v[94:95], v[188:189]
	v_pk_add_f32 v[96:97], v[96:97], v[190:191]
	v_pk_add_f32 v[90:91], v[90:91], v[192:193]
	v_pk_add_f32 v[92:93], v[92:93], v[194:195]
	global_store_dwordx4 v241, v[94:97], s[34:35]
	global_store_dwordx4 v241, v[90:93], s[34:35] offset:16
	v_fmac_f32_e32 v146, v94, v94
	v_fmac_f32_e32 v146, v95, v95
	v_fmac_f32_e32 v146, v96, v96
	v_fmac_f32_e32 v146, v97, v97
	v_fmac_f32_e32 v146, v90, v90
	v_fmac_f32_e32 v146, v91, v91
	v_fmac_f32_e32 v146, v92, v92
	v_fmac_f32_e32 v146, v93, v93
	v_pk_mul_f32 v[188:189], v[94:95], v[228:229]
	v_pk_mul_f32 v[190:191], v[96:97], v[230:231]
	v_pk_mul_f32 v[192:193], v[90:91], v[232:233]
	v_pk_mul_f32 v[194:195], v[92:93], v[234:235]
	v_cvt_pk_bf16_f32 v188, v188, v189
	v_cvt_pk_bf16_f32 v189, v190, v191
	v_cvt_pk_bf16_f32 v190, v192, v193
	v_cvt_pk_bf16_f32 v191, v194, v195
	v_lshrrev_b32_e32 v192, 1, v241
	global_store_dwordx4 v192, v[188:191], s[20:21]
	s_nop 0
	global_load_dwordx4 v[188:191], v240, s[6:7]
	global_load_dwordx4 v[192:195], v240, s[6:7] offset:16
	s_waitcnt vmcnt(25)
	v_pk_add_f32 v[86:87], v[86:87], v[196:197]
	v_pk_add_f32 v[88:89], v[88:89], v[198:199]
	v_pk_add_f32 v[82:83], v[82:83], v[224:225]
	v_pk_add_f32 v[84:85], v[84:85], v[226:227]
	global_store_dwordx4 v241, v[86:89], s[34:35] offset:512
	global_store_dwordx4 v241, v[82:85], s[34:35] offset:528
	v_fmac_f32_e32 v146, v86, v86
	v_fmac_f32_e32 v146, v87, v87
	v_fmac_f32_e32 v146, v88, v88
	v_fmac_f32_e32 v146, v89, v89
	v_fmac_f32_e32 v146, v82, v82
	v_fmac_f32_e32 v146, v83, v83
	v_fmac_f32_e32 v146, v84, v84
	v_fmac_f32_e32 v146, v85, v85
	v_pk_mul_f32 v[196:197], v[86:87], v[236:237]
	v_pk_mul_f32 v[198:199], v[88:89], v[238:239]
	v_pk_mul_f32 v[224:225], v[82:83], v[140:141]
	v_pk_mul_f32 v[226:227], v[84:85], v[142:143]
	v_cvt_pk_bf16_f32 v196, v196, v197
	v_cvt_pk_bf16_f32 v197, v198, v199
	v_cvt_pk_bf16_f32 v198, v224, v225
	v_cvt_pk_bf16_f32 v199, v226, v227
	v_lshrrev_b32_e32 v224, 1, v241
	global_store_dwordx4 v224, v[196:199], s[20:21] offset:256
	v_add_u32_e32 v241, 0x20000, v241
	global_load_dwordx4 v[196:199], v240, s[6:7] offset:512
	global_load_dwordx4 v[224:227], v240, s[6:7] offset:528
	v_add_u32_e32 v240, 0x20000, v240
	s_waitcnt vmcnt(25)
	v_pk_add_f32 v[78:79], v[78:79], v[156:157]
	v_pk_add_f32 v[80:81], v[80:81], v[158:159]
	v_pk_add_f32 v[74:75], v[74:75], v[160:161]
	v_pk_add_f32 v[76:77], v[76:77], v[162:163]
	global_store_dwordx4 v241, v[78:81], s[34:35]
	global_store_dwordx4 v241, v[74:77], s[34:35] offset:16
	v_fmac_f32_e32 v147, v78, v78
	v_fmac_f32_e32 v147, v79, v79
	v_fmac_f32_e32 v147, v80, v80
	v_fmac_f32_e32 v147, v81, v81
	v_fmac_f32_e32 v147, v74, v74
	v_fmac_f32_e32 v147, v75, v75
	v_fmac_f32_e32 v147, v76, v76
	v_fmac_f32_e32 v147, v77, v77
	v_pk_mul_f32 v[156:157], v[78:79], v[228:229]
	v_pk_mul_f32 v[158:159], v[80:81], v[230:231]
	v_pk_mul_f32 v[160:161], v[74:75], v[232:233]
	v_pk_mul_f32 v[162:163], v[76:77], v[234:235]
	v_cvt_pk_bf16_f32 v156, v156, v157
	v_cvt_pk_bf16_f32 v157, v158, v159
	v_cvt_pk_bf16_f32 v158, v160, v161
	v_cvt_pk_bf16_f32 v159, v162, v163
	v_lshrrev_b32_e32 v160, 1, v241
	global_store_dwordx4 v160, v[156:159], s[20:21]
	s_nop 0
	global_load_dwordx4 v[156:159], v240, s[6:7]
	global_load_dwordx4 v[160:163], v240, s[6:7] offset:16
	s_waitcnt vmcnt(25)
	v_pk_add_f32 v[70:71], v[70:71], v[164:165]
	v_pk_add_f32 v[72:73], v[72:73], v[166:167]
	v_pk_add_f32 v[66:67], v[66:67], v[168:169]
	v_pk_add_f32 v[68:69], v[68:69], v[170:171]
	global_store_dwordx4 v241, v[70:73], s[34:35] offset:512
	global_store_dwordx4 v241, v[66:69], s[34:35] offset:528
	v_fmac_f32_e32 v147, v70, v70
	v_fmac_f32_e32 v147, v71, v71
	v_fmac_f32_e32 v147, v72, v72
	v_fmac_f32_e32 v147, v73, v73
	v_fmac_f32_e32 v147, v66, v66
	v_fmac_f32_e32 v147, v67, v67
	v_fmac_f32_e32 v147, v68, v68
	v_fmac_f32_e32 v147, v69, v69
	v_pk_mul_f32 v[164:165], v[70:71], v[236:237]
	v_pk_mul_f32 v[166:167], v[72:73], v[238:239]
	v_pk_mul_f32 v[168:169], v[66:67], v[140:141]
	v_pk_mul_f32 v[170:171], v[68:69], v[142:143]
	v_cvt_pk_bf16_f32 v164, v164, v165
	v_cvt_pk_bf16_f32 v165, v166, v167
	v_cvt_pk_bf16_f32 v166, v168, v169
	v_cvt_pk_bf16_f32 v167, v170, v171
	v_lshrrev_b32_e32 v168, 1, v241
	global_store_dwordx4 v168, v[164:167], s[20:21] offset:256
	v_add_u32_e32 v241, 0xa0000, v241
	global_load_dwordx4 v[164:167], v240, s[6:7] offset:512
	global_load_dwordx4 v[168:171], v240, s[6:7] offset:528
	v_add_u32_e32 v240, 0x20000, v240
	s_waitcnt vmcnt(25)
	v_pk_add_f32 v[62:63], v[62:63], v[172:173]
	v_pk_add_f32 v[64:65], v[64:65], v[174:175]
	v_pk_add_f32 v[58:59], v[58:59], v[176:177]
	v_pk_add_f32 v[60:61], v[60:61], v[178:179]
	global_store_dwordx4 v241, v[62:65], s[34:35]
	global_store_dwordx4 v241, v[58:61], s[34:35] offset:16
	v_fmac_f32_e32 v148, v62, v62
	v_fmac_f32_e32 v148, v63, v63
	v_fmac_f32_e32 v148, v64, v64
	v_fmac_f32_e32 v148, v65, v65
	v_fmac_f32_e32 v148, v58, v58
	v_fmac_f32_e32 v148, v59, v59
	v_fmac_f32_e32 v148, v60, v60
	v_fmac_f32_e32 v148, v61, v61
	v_pk_mul_f32 v[172:173], v[62:63], v[228:229]
	v_pk_mul_f32 v[174:175], v[64:65], v[230:231]
	v_pk_mul_f32 v[176:177], v[58:59], v[232:233]
	v_pk_mul_f32 v[178:179], v[60:61], v[234:235]
	v_cvt_pk_bf16_f32 v172, v172, v173
	v_cvt_pk_bf16_f32 v173, v174, v175
	v_cvt_pk_bf16_f32 v174, v176, v177
	v_cvt_pk_bf16_f32 v175, v178, v179
	v_lshrrev_b32_e32 v176, 1, v241
	global_store_dwordx4 v176, v[172:175], s[20:21]
	s_nop 0
	global_load_dwordx4 v[172:175], v240, s[6:7]
	global_load_dwordx4 v[176:179], v240, s[6:7] offset:16
	s_waitcnt vmcnt(25)
	v_pk_add_f32 v[54:55], v[54:55], v[180:181]
	v_pk_add_f32 v[56:57], v[56:57], v[182:183]
	v_pk_add_f32 v[50:51], v[50:51], v[184:185]
	v_pk_add_f32 v[52:53], v[52:53], v[186:187]
	global_store_dwordx4 v241, v[54:57], s[34:35] offset:512
	global_store_dwordx4 v241, v[50:53], s[34:35] offset:528
	v_fmac_f32_e32 v148, v54, v54
	v_fmac_f32_e32 v148, v55, v55
	v_fmac_f32_e32 v148, v56, v56
	v_fmac_f32_e32 v148, v57, v57
	v_fmac_f32_e32 v148, v50, v50
	v_fmac_f32_e32 v148, v51, v51
	v_fmac_f32_e32 v148, v52, v52
	v_fmac_f32_e32 v148, v53, v53
	v_pk_mul_f32 v[180:181], v[54:55], v[236:237]
	v_pk_mul_f32 v[182:183], v[56:57], v[238:239]
	v_pk_mul_f32 v[184:185], v[50:51], v[140:141]
	v_pk_mul_f32 v[186:187], v[52:53], v[142:143]
	v_cvt_pk_bf16_f32 v180, v180, v181
	v_cvt_pk_bf16_f32 v181, v182, v183
	v_cvt_pk_bf16_f32 v182, v184, v185
	v_cvt_pk_bf16_f32 v183, v186, v187
	v_lshrrev_b32_e32 v184, 1, v241
	global_store_dwordx4 v184, v[180:183], s[20:21] offset:256
	v_add_u32_e32 v241, 0x20000, v241
	global_load_dwordx4 v[180:183], v240, s[6:7] offset:512
	global_load_dwordx4 v[184:187], v240, s[6:7] offset:528
	s_waitcnt vmcnt(25)
	v_pk_add_f32 v[46:47], v[46:47], v[188:189]
	v_pk_add_f32 v[48:49], v[48:49], v[190:191]
	v_pk_add_f32 v[42:43], v[42:43], v[192:193]
	v_pk_add_f32 v[44:45], v[44:45], v[194:195]
	global_store_dwordx4 v241, v[46:49], s[34:35]
	global_store_dwordx4 v241, v[42:45], s[34:35] offset:16
	v_fmac_f32_e32 v149, v46, v46
	v_fmac_f32_e32 v149, v47, v47
	v_fmac_f32_e32 v149, v48, v48
	v_fmac_f32_e32 v149, v49, v49
	v_fmac_f32_e32 v149, v42, v42
	v_fmac_f32_e32 v149, v43, v43
	v_fmac_f32_e32 v149, v44, v44
	v_fmac_f32_e32 v149, v45, v45
	v_pk_mul_f32 v[188:189], v[46:47], v[228:229]
	v_pk_mul_f32 v[190:191], v[48:49], v[230:231]
	v_pk_mul_f32 v[192:193], v[42:43], v[232:233]
	v_pk_mul_f32 v[194:195], v[44:45], v[234:235]
	v_cvt_pk_bf16_f32 v188, v188, v189
	v_cvt_pk_bf16_f32 v189, v190, v191
	v_cvt_pk_bf16_f32 v190, v192, v193
	v_cvt_pk_bf16_f32 v191, v194, v195
	v_lshrrev_b32_e32 v192, 1, v241
	global_store_dwordx4 v192, v[188:191], s[20:21]
	s_nop 0
	s_waitcnt vmcnt(23)
	v_pk_add_f32 v[38:39], v[38:39], v[196:197]
	v_pk_add_f32 v[40:41], v[40:41], v[198:199]
	v_pk_add_f32 v[34:35], v[34:35], v[224:225]
	v_pk_add_f32 v[36:37], v[36:37], v[226:227]
	global_store_dwordx4 v241, v[38:41], s[34:35] offset:512
	global_store_dwordx4 v241, v[34:37], s[34:35] offset:528
	v_fmac_f32_e32 v149, v38, v38
	v_fmac_f32_e32 v149, v39, v39
	v_fmac_f32_e32 v149, v40, v40
	v_fmac_f32_e32 v149, v41, v41
	v_fmac_f32_e32 v149, v34, v34
	v_fmac_f32_e32 v149, v35, v35
	v_fmac_f32_e32 v149, v36, v36
	v_fmac_f32_e32 v149, v37, v37
	v_pk_mul_f32 v[196:197], v[38:39], v[236:237]
	v_pk_mul_f32 v[198:199], v[40:41], v[238:239]
	v_pk_mul_f32 v[224:225], v[34:35], v[140:141]
	v_pk_mul_f32 v[226:227], v[36:37], v[142:143]
	v_cvt_pk_bf16_f32 v196, v196, v197
	v_cvt_pk_bf16_f32 v197, v198, v199
	v_cvt_pk_bf16_f32 v198, v224, v225
	v_cvt_pk_bf16_f32 v199, v226, v227
	v_lshrrev_b32_e32 v224, 1, v241
	global_store_dwordx4 v224, v[196:199], s[20:21] offset:256
	v_add_u32_e32 v241, 0x20000, v241
	s_waitcnt vmcnt(21)
	v_pk_add_f32 v[30:31], v[30:31], v[156:157]
	v_pk_add_f32 v[32:33], v[32:33], v[158:159]
	v_pk_add_f32 v[26:27], v[26:27], v[160:161]
	v_pk_add_f32 v[28:29], v[28:29], v[162:163]
	global_store_dwordx4 v241, v[30:33], s[34:35]
	global_store_dwordx4 v241, v[26:29], s[34:35] offset:16
	v_fmac_f32_e32 v150, v30, v30
	v_fmac_f32_e32 v150, v31, v31
	v_fmac_f32_e32 v150, v32, v32
	v_fmac_f32_e32 v150, v33, v33
	v_fmac_f32_e32 v150, v26, v26
	v_fmac_f32_e32 v150, v27, v27
	v_fmac_f32_e32 v150, v28, v28
	v_fmac_f32_e32 v150, v29, v29
	v_pk_mul_f32 v[156:157], v[30:31], v[228:229]
	v_pk_mul_f32 v[158:159], v[32:33], v[230:231]
	v_pk_mul_f32 v[160:161], v[26:27], v[232:233]
	v_pk_mul_f32 v[162:163], v[28:29], v[234:235]
	v_cvt_pk_bf16_f32 v156, v156, v157
	v_cvt_pk_bf16_f32 v157, v158, v159
	v_cvt_pk_bf16_f32 v158, v160, v161
	v_cvt_pk_bf16_f32 v159, v162, v163
	v_lshrrev_b32_e32 v160, 1, v241
	global_store_dwordx4 v160, v[156:159], s[20:21]
	s_nop 0
	s_waitcnt vmcnt(19)
	v_pk_add_f32 v[22:23], v[22:23], v[164:165]
	v_pk_add_f32 v[24:25], v[24:25], v[166:167]
	v_pk_add_f32 v[18:19], v[18:19], v[168:169]
	v_pk_add_f32 v[20:21], v[20:21], v[170:171]
	global_store_dwordx4 v241, v[22:25], s[34:35] offset:512
	global_store_dwordx4 v241, v[18:21], s[34:35] offset:528
	v_fmac_f32_e32 v150, v22, v22
	v_fmac_f32_e32 v150, v23, v23
	v_fmac_f32_e32 v150, v24, v24
	v_fmac_f32_e32 v150, v25, v25
	v_fmac_f32_e32 v150, v18, v18
	v_fmac_f32_e32 v150, v19, v19
	v_fmac_f32_e32 v150, v20, v20
	v_fmac_f32_e32 v150, v21, v21
	v_pk_mul_f32 v[164:165], v[22:23], v[236:237]
	v_pk_mul_f32 v[166:167], v[24:25], v[238:239]
	v_pk_mul_f32 v[168:169], v[18:19], v[140:141]
	v_pk_mul_f32 v[170:171], v[20:21], v[142:143]
	v_cvt_pk_bf16_f32 v164, v164, v165
	v_cvt_pk_bf16_f32 v165, v166, v167
	v_cvt_pk_bf16_f32 v166, v168, v169
	v_cvt_pk_bf16_f32 v167, v170, v171
	v_lshrrev_b32_e32 v168, 1, v241
	global_store_dwordx4 v168, v[164:167], s[20:21] offset:256
	v_add_u32_e32 v241, 0x20000, v241
	s_waitcnt vmcnt(17)
	v_pk_add_f32 v[14:15], v[14:15], v[172:173]
	v_pk_add_f32 v[16:17], v[16:17], v[174:175]
	v_pk_add_f32 v[10:11], v[10:11], v[176:177]
	v_pk_add_f32 v[12:13], v[12:13], v[178:179]
	global_store_dwordx4 v241, v[14:17], s[34:35]
	global_store_dwordx4 v241, v[10:13], s[34:35] offset:16
	v_fmac_f32_e32 v151, v14, v14
	v_fmac_f32_e32 v151, v15, v15
	v_fmac_f32_e32 v151, v16, v16
	v_fmac_f32_e32 v151, v17, v17
	v_fmac_f32_e32 v151, v10, v10
	v_fmac_f32_e32 v151, v11, v11
	v_fmac_f32_e32 v151, v12, v12
	v_fmac_f32_e32 v151, v13, v13
	v_pk_mul_f32 v[172:173], v[14:15], v[228:229]
	v_pk_mul_f32 v[174:175], v[16:17], v[230:231]
	v_pk_mul_f32 v[176:177], v[10:11], v[232:233]
	v_pk_mul_f32 v[178:179], v[12:13], v[234:235]
	v_cvt_pk_bf16_f32 v172, v172, v173
	v_cvt_pk_bf16_f32 v173, v174, v175
	v_cvt_pk_bf16_f32 v174, v176, v177
	v_cvt_pk_bf16_f32 v175, v178, v179
	v_lshrrev_b32_e32 v176, 1, v241
	global_store_dwordx4 v176, v[172:175], s[20:21]
	s_nop 0
	s_waitcnt vmcnt(15)
	v_pk_add_f32 v[6:7], v[6:7], v[180:181]
	v_pk_add_f32 v[8:9], v[8:9], v[182:183]
	v_pk_add_f32 v[2:3], v[2:3], v[184:185]
	v_pk_add_f32 v[4:5], v[4:5], v[186:187]
	global_store_dwordx4 v241, v[6:9], s[34:35] offset:512
	global_store_dwordx4 v241, v[2:5], s[34:35] offset:528
	v_fmac_f32_e32 v151, v6, v6
	v_fmac_f32_e32 v151, v7, v7
	v_fmac_f32_e32 v151, v8, v8
	v_fmac_f32_e32 v151, v9, v9
	v_fmac_f32_e32 v151, v2, v2
	v_fmac_f32_e32 v151, v3, v3
	v_fmac_f32_e32 v151, v4, v4
	v_fmac_f32_e32 v151, v5, v5
	v_pk_mul_f32 v[180:181], v[6:7], v[236:237]
	v_pk_mul_f32 v[182:183], v[8:9], v[238:239]
	v_pk_mul_f32 v[184:185], v[2:3], v[140:141]
	v_pk_mul_f32 v[186:187], v[4:5], v[142:143]
	v_cvt_pk_bf16_f32 v180, v180, v181
	v_cvt_pk_bf16_f32 v181, v182, v183
	v_cvt_pk_bf16_f32 v182, v184, v185
	v_cvt_pk_bf16_f32 v183, v186, v187
	v_lshrrev_b32_e32 v184, 1, v241
	global_store_dwordx4 v184, v[180:183], s[20:21] offset:256
	s_nop 0
	v_xor_b32_e32 v156, 16, v217
	v_xor_b32_e32 v157, 32, v217
	v_lshlrev_b32_e32 v156, 2, v156
	v_lshlrev_b32_e32 v157, 2, v157
	ds_bpermute_b32 v160, v156, v144
	ds_bpermute_b32 v161, v156, v145
	ds_bpermute_b32 v162, v156, v146
	ds_bpermute_b32 v163, v156, v147
	ds_bpermute_b32 v164, v156, v148
	ds_bpermute_b32 v165, v156, v149
	ds_bpermute_b32 v166, v156, v150
	ds_bpermute_b32 v167, v156, v151
	s_waitcnt lgkmcnt(0)
	v_add_f32_e32 v144, v144, v160
	v_add_f32_e32 v145, v145, v161
	v_add_f32_e32 v146, v146, v162
	v_add_f32_e32 v147, v147, v163
	v_add_f32_e32 v148, v148, v164
	v_add_f32_e32 v149, v149, v165
	v_add_f32_e32 v150, v150, v166
	v_add_f32_e32 v151, v151, v167
	ds_bpermute_b32 v160, v157, v144
	ds_bpermute_b32 v161, v157, v145
	ds_bpermute_b32 v162, v157, v146
	ds_bpermute_b32 v163, v157, v147
	ds_bpermute_b32 v164, v157, v148
	ds_bpermute_b32 v165, v157, v149
	ds_bpermute_b32 v166, v157, v150
	ds_bpermute_b32 v167, v157, v151
	s_waitcnt lgkmcnt(0)
	v_add_f32_e32 v144, v144, v160
	v_add_f32_e32 v145, v145, v161
	v_add_f32_e32 v146, v146, v162
	v_add_f32_e32 v147, v147, v163
	v_add_f32_e32 v148, v148, v164
	v_add_f32_e32 v149, v149, v165
	v_add_f32_e32 v150, v150, v166
	v_add_f32_e32 v151, v151, v167
	v_lshl_add_u32 v158, s40, 8, v152
	v_lshlrev_b32_e32 v158, 2, v158
	s_and_saveexec_b64 s[2:3], s[0:1]
	global_atomic_add_f32 v158, v144, s[18:19]
	global_atomic_add_f32 v158, v145, s[18:19] offset:64
	global_atomic_add_f32 v158, v146, s[18:19] offset:128
	global_atomic_add_f32 v158, v147, s[18:19] offset:192
	global_atomic_add_f32 v158, v148, s[18:19] offset:512
	global_atomic_add_f32 v158, v149, s[18:19] offset:576
	global_atomic_add_f32 v158, v150, s[18:19] offset:640
	global_atomic_add_f32 v158, v151, s[18:19] offset:704
	s_or_b64 exec, exec, s[2:3]
	s_branch .LBB0_1111
.Lout_plain:
	s_nop 3
	global_load_dwordx4 v[156:159], v240, s[6:7]
	global_load_dwordx4 v[160:163], v240, s[6:7] offset:16
	global_load_dwordx4 v[164:167], v240, s[6:7] offset:512
	global_load_dwordx4 v[168:171], v240, s[6:7] offset:528
	v_add_u32_e32 v240, 0x20000, v240
	global_load_dwordx4 v[172:175], v240, s[6:7]
	global_load_dwordx4 v[176:179], v240, s[6:7] offset:16
	global_load_dwordx4 v[180:183], v240, s[6:7] offset:512
	global_load_dwordx4 v[184:187], v240, s[6:7] offset:528
	v_add_u32_e32 v240, 0x20000, v240
	global_load_dwordx4 v[188:191], v240, s[6:7]
	global_load_dwordx4 v[192:195], v240, s[6:7] offset:16
	global_load_dwordx4 v[196:199], v240, s[6:7] offset:512
	global_load_dwordx4 v[224:227], v240, s[6:7] offset:528
	v_add_u32_e32 v240, 0x20000, v240
	s_waitcnt vmcnt(10)
	v_pk_add_f32 v[126:127], v[126:127], v[156:157]
	v_pk_add_f32 v[128:129], v[128:129], v[158:159]
	v_pk_add_f32 v[122:123], v[122:123], v[160:161]
	v_pk_add_f32 v[124:125], v[124:125], v[162:163]
	global_store_dwordx4 v241, v[126:129], s[34:35]
	global_store_dwordx4 v241, v[122:125], s[34:35] offset:16
	global_load_dwordx4 v[156:159], v240, s[6:7]
	global_load_dwordx4 v[160:163], v240, s[6:7] offset:16
	s_waitcnt vmcnt(12)
	v_pk_add_f32 v[118:119], v[118:119], v[164:165]
	v_pk_add_f32 v[120:121], v[120:121], v[166:167]
	v_pk_add_f32 v[114:115], v[114:115], v[168:169]
	v_pk_add_f32 v[116:117], v[116:117], v[170:171]
	global_store_dwordx4 v241, v[118:121], s[34:35] offset:512
	global_store_dwordx4 v241, v[114:117], s[34:35] offset:528
	v_add_u32_e32 v241, 0x20000, v241
	global_load_dwordx4 v[164:167], v240, s[6:7] offset:512
	global_load_dwordx4 v[168:171], v240, s[6:7] offset:528
	v_add_u32_e32 v240, 0xa0000, v240
	s_waitcnt vmcnt(14)
	v_pk_add_f32 v[110:111], v[110:111], v[172:173]
	v_pk_add_f32 v[112:113], v[112:113], v[174:175]
	v_pk_add_f32 v[106:107], v[106:107], v[176:177]
	v_pk_add_f32 v[108:109], v[108:109], v[178:179]
	global_store_dwordx4 v241, v[110:113], s[34:35]
	global_store_dwordx4 v241, v[106:109], s[34:35] offset:16
	global_load_dwordx4 v[172:175], v240, s[6:7]
	global_load_dwordx4 v[176:179], v240, s[6:7] offset:16
	s_waitcnt vmcnt(16)
	v_pk_add_f32 v[102:103], v[102:103], v[180:181]
	v_pk_add_f32 v[104:105], v[104:105], v[182:183]
	v_pk_add_f32 v[98:99], v[98:99], v[184:185]
	v_pk_add_f32 v[100:101], v[100:101], v[186:187]
	global_store_dwordx4 v241, v[102:105], s[34:35] offset:512
	global_store_dwordx4 v241, v[98:101], s[34:35] offset:528
	v_add_u32_e32 v241, 0x20000, v241
	global_load_dwordx4 v[180:183], v240, s[6:7] offset:512
	global_load_dwordx4 v[184:187], v240, s[6:7] offset:528
	v_add_u32_e32 v240, 0x20000, v240
	s_waitcnt vmcnt(18)
	v_pk_add_f32 v[94:95], v[94:95], v[188:189]
	v_pk_add_f32 v[96:97], v[96:97], v[190:191]
	v_pk_add_f32 v[90:91], v[90:91], v[192:193]
	v_pk_add_f32 v[92:93], v[92:93], v[194:195]
	global_store_dwordx4 v241, v[94:97], s[34:35]
	global_store_dwordx4 v241, v[90:93], s[34:35] offset:16
	global_load_dwordx4 v[188:191], v240, s[6:7]
	global_load_dwordx4 v[192:195], v240, s[6:7] offset:16
	s_waitcnt vmcnt(20)
	v_pk_add_f32 v[86:87], v[86:87], v[196:197]
	v_pk_add_f32 v[88:89], v[88:89], v[198:199]
	v_pk_add_f32 v[82:83], v[82:83], v[224:225]
	v_pk_add_f32 v[84:85], v[84:85], v[226:227]
	global_store_dwordx4 v241, v[86:89], s[34:35] offset:512
	global_store_dwordx4 v241, v[82:85], s[34:35] offset:528
	v_add_u32_e32 v241, 0x20000, v241
	global_load_dwordx4 v[196:199], v240, s[6:7] offset:512
	global_load_dwordx4 v[224:227], v240, s[6:7] offset:528
	v_add_u32_e32 v240, 0x20000, v240
	s_waitcnt vmcnt(20)
	v_pk_add_f32 v[78:79], v[78:79], v[156:157]
	v_pk_add_f32 v[80:81], v[80:81], v[158:159]
	v_pk_add_f32 v[74:75], v[74:75], v[160:161]
	v_pk_add_f32 v[76:77], v[76:77], v[162:163]
	global_store_dwordx4 v241, v[78:81], s[34:35]
	global_store_dwordx4 v241, v[74:77], s[34:35] offset:16
	global_load_dwordx4 v[156:159], v240, s[6:7]
	global_load_dwordx4 v[160:163], v240, s[6:7] offset:16
	s_waitcnt vmcnt(20)
	v_pk_add_f32 v[70:71], v[70:71], v[164:165]
	v_pk_add_f32 v[72:73], v[72:73], v[166:167]
	v_pk_add_f32 v[66:67], v[66:67], v[168:169]
	v_pk_add_f32 v[68:69], v[68:69], v[170:171]
	global_store_dwordx4 v241, v[70:73], s[34:35] offset:512
	global_store_dwordx4 v241, v[66:69], s[34:35] offset:528
	v_add_u32_e32 v241, 0xa0000, v241
	global_load_dwordx4 v[164:167], v240, s[6:7] offset:512
	global_load_dwordx4 v[168:171], v240, s[6:7] offset:528
	v_add_u32_e32 v240, 0x20000, v240
	s_waitcnt vmcnt(20)
	v_pk_add_f32 v[62:63], v[62:63], v[172:173]
	v_pk_add_f32 v[64:65], v[64:65], v[174:175]
	v_pk_add_f32 v[58:59], v[58:59], v[176:177]
	v_pk_add_f32 v[60:61], v[60:61], v[178:179]
	global_store_dwordx4 v241, v[62:65], s[34:35]
	global_store_dwordx4 v241, v[58:61], s[34:35] offset:16
	global_load_dwordx4 v[172:175], v240, s[6:7]
	global_load_dwordx4 v[176:179], v240, s[6:7] offset:16
	s_waitcnt vmcnt(20)
	v_pk_add_f32 v[54:55], v[54:55], v[180:181]
	v_pk_add_f32 v[56:57], v[56:57], v[182:183]
	v_pk_add_f32 v[50:51], v[50:51], v[184:185]
	v_pk_add_f32 v[52:53], v[52:53], v[186:187]
	global_store_dwordx4 v241, v[54:57], s[34:35] offset:512
	global_store_dwordx4 v241, v[50:53], s[34:35] offset:528
	v_add_u32_e32 v241, 0x20000, v241
	global_load_dwordx4 v[180:183], v240, s[6:7] offset:512
	global_load_dwordx4 v[184:187], v240, s[6:7] offset:528
	s_waitcnt vmcnt(20)
	v_pk_add_f32 v[46:47], v[46:47], v[188:189]
	v_pk_add_f32 v[48:49], v[48:49], v[190:191]
	v_pk_add_f32 v[42:43], v[42:43], v[192:193]
	v_pk_add_f32 v[44:45], v[44:45], v[194:195]
	global_store_dwordx4 v241, v[46:49], s[34:35]
	global_store_dwordx4 v241, v[42:45], s[34:35] offset:16
	s_waitcnt vmcnt(18)
	v_pk_add_f32 v[38:39], v[38:39], v[196:197]
	v_pk_add_f32 v[40:41], v[40:41], v[198:199]
	v_pk_add_f32 v[34:35], v[34:35], v[224:225]
	v_pk_add_f32 v[36:37], v[36:37], v[226:227]
	global_store_dwordx4 v241, v[38:41], s[34:35] offset:512
	global_store_dwordx4 v241, v[34:37], s[34:35] offset:528
	v_add_u32_e32 v241, 0x20000, v241
	s_waitcnt vmcnt(16)
	v_pk_add_f32 v[30:31], v[30:31], v[156:157]
	v_pk_add_f32 v[32:33], v[32:33], v[158:159]
	v_pk_add_f32 v[26:27], v[26:27], v[160:161]
	v_pk_add_f32 v[28:29], v[28:29], v[162:163]
	global_store_dwordx4 v241, v[30:33], s[34:35]
	global_store_dwordx4 v241, v[26:29], s[34:35] offset:16
	s_waitcnt vmcnt(14)
	v_pk_add_f32 v[22:23], v[22:23], v[164:165]
	v_pk_add_f32 v[24:25], v[24:25], v[166:167]
	v_pk_add_f32 v[18:19], v[18:19], v[168:169]
	v_pk_add_f32 v[20:21], v[20:21], v[170:171]
	global_store_dwordx4 v241, v[22:25], s[34:35] offset:512
	global_store_dwordx4 v241, v[18:21], s[34:35] offset:528
	v_add_u32_e32 v241, 0x20000, v241
	s_waitcnt vmcnt(12)
	v_pk_add_f32 v[14:15], v[14:15], v[172:173]
	v_pk_add_f32 v[16:17], v[16:17], v[174:175]
	v_pk_add_f32 v[10:11], v[10:11], v[176:177]
	v_pk_add_f32 v[12:13], v[12:13], v[178:179]
	global_store_dwordx4 v241, v[14:17], s[34:35]
	global_store_dwordx4 v241, v[10:13], s[34:35] offset:16
	s_waitcnt vmcnt(10)
	v_pk_add_f32 v[6:7], v[6:7], v[180:181]
	v_pk_add_f32 v[8:9], v[8:9], v[182:183]
	v_pk_add_f32 v[2:3], v[2:3], v[184:185]
	v_pk_add_f32 v[4:5], v[4:5], v[186:187]
	global_store_dwordx4 v241, v[6:9], s[34:35] offset:512
	global_store_dwordx4 v241, v[2:5], s[34:35] offset:528
